# MoBA output epilogue: neighbour exchange through DPP quad_perm instead of one LDS round trip per stored dword
# speedup vs baseline: 1.0364x; 1.0021x over previous
.LBB0_654:
	s_or_b64 exec, exec, s[2:3]
	v_ashrrev_i32_e32 v83, 3, v80
	s_waitcnt lgkmcnt(0)
	v_rcp_f32_e32 v84, v76
	v_lshlrev_b32_e32 v82, 1, v81
	v_lshlrev_b32_e32 v81, 2, v83
	v_and_b32_e32 v81, -16, v81
	v_add_u32_e32 v83, s46, v81
	v_lshlrev_b32_e32 v76, 2, v80
	ds_read_b32 v81, v83 offset:256
	v_xor_b32_e32 v76, 4, v76
	v_mul_f32_e32 v16, v16, v84
	s_nop 1
	v_mov_b32_dpp v85, v16 quad_perm:[1,0,3,2] row_mask:0xf bank_mask:0xf
	v_and_b32_e32 v80, 1, v80
	s_waitcnt lgkmcnt(0)
	v_lshl_or_b32 v160, v81, 8, v82
	v_cmp_eq_u32_e32 vcc, 0, v80
	v_lshl_add_u64 v[80:81], s[12:13], 0, v[160:161]
	s_and_saveexec_b64 s[2:3], vcc
	s_cbranch_execz .LBB0_656
	s_waitcnt lgkmcnt(0)
	v_cvt_pk_bf16_f32 v16, v16, v85
	global_store_dword v[80:81], v16, off
.LBB0_656:
	s_or_b64 exec, exec, s[2:3]
	v_mul_f32_e32 v16, v32, v84
	s_nop 1
	v_mov_b32_dpp v32, v16 quad_perm:[1,0,3,2] row_mask:0xf bank_mask:0xf
	s_and_saveexec_b64 s[2:3], vcc
	s_cbranch_execz .LBB0_658
	s_waitcnt lgkmcnt(0)
	v_cvt_pk_bf16_f32 v16, v16, v32
	global_store_dword v[80:81], v16, off offset:64
.LBB0_658:
	s_or_b64 exec, exec, s[2:3]
	v_mul_f32_e32 v16, v48, v84
	s_waitcnt lgkmcnt(0)
	s_nop 1
	v_mov_b32_dpp v32, v16 quad_perm:[1,0,3,2] row_mask:0xf bank_mask:0xf
	s_and_saveexec_b64 s[2:3], vcc
	s_cbranch_execz .LBB0_660
	s_waitcnt lgkmcnt(0)
	v_cvt_pk_bf16_f32 v16, v16, v32
	global_store_dword v[80:81], v16, off offset:128
.LBB0_660:
	s_or_b64 exec, exec, s[2:3]
	v_mul_f32_e32 v0, v0, v84
	s_nop 1
	v_mov_b32_dpp v16, v0 quad_perm:[1,0,3,2] row_mask:0xf bank_mask:0xf
	s_and_saveexec_b64 s[2:3], vcc
	s_cbranch_execz .LBB0_662
	s_waitcnt lgkmcnt(0)
	v_cvt_pk_bf16_f32 v0, v0, v16
	global_store_dword v[80:81], v0, off offset:192
.LBB0_662:
	s_or_b64 exec, exec, s[2:3]
	v_rcp_f32_e32 v0, v77
	s_waitcnt lgkmcnt(0)
	ds_read_b32 v16, v83 offset:260
	v_mul_f32_e32 v32, v17, v0
	s_nop 1
	v_mov_b32_dpp v48, v32 quad_perm:[1,0,3,2] row_mask:0xf bank_mask:0xf
	s_waitcnt lgkmcnt(0)
	v_lshl_or_b32 v160, v16, 8, v82
	v_lshl_add_u64 v[16:17], s[12:13], 0, v[160:161]
	s_and_saveexec_b64 s[2:3], vcc
	s_cbranch_execz .LBB0_664
	s_waitcnt lgkmcnt(0)
	v_cvt_pk_bf16_f32 v32, v32, v48
	global_store_dword v[16:17], v32, off
.LBB0_664:
	s_or_b64 exec, exec, s[2:3]
	v_mul_f32_e32 v32, v33, v0
	s_nop 1
	v_mov_b32_dpp v33, v32 quad_perm:[1,0,3,2] row_mask:0xf bank_mask:0xf
	s_and_saveexec_b64 s[2:3], vcc
	s_cbranch_execz .LBB0_666
	s_waitcnt lgkmcnt(0)
	v_cvt_pk_bf16_f32 v32, v32, v33
	global_store_dword v[16:17], v32, off offset:64
.LBB0_666:
	s_or_b64 exec, exec, s[2:3]
	v_mul_f32_e32 v32, v49, v0
	s_waitcnt lgkmcnt(0)
	s_nop 1
	v_mov_b32_dpp v33, v32 quad_perm:[1,0,3,2] row_mask:0xf bank_mask:0xf
	s_and_saveexec_b64 s[2:3], vcc
	s_cbranch_execz .LBB0_668
	s_waitcnt lgkmcnt(0)
	v_cvt_pk_bf16_f32 v32, v32, v33
	global_store_dword v[16:17], v32, off offset:128
.LBB0_668:
	s_or_b64 exec, exec, s[2:3]
	v_mul_f32_e32 v0, v1, v0
	s_nop 1
	v_mov_b32_dpp v1, v0 quad_perm:[1,0,3,2] row_mask:0xf bank_mask:0xf
	s_and_saveexec_b64 s[2:3], vcc
	s_cbranch_execz .LBB0_670
	s_waitcnt lgkmcnt(0)
	v_cvt_pk_bf16_f32 v0, v0, v1
	global_store_dword v[16:17], v0, off offset:192
.LBB0_670:
	s_or_b64 exec, exec, s[2:3]
	v_rcp_f32_e32 v16, v78
	ds_read_b32 v0, v83 offset:264
	v_mul_f32_e32 v17, v18, v16
	s_nop 1
	v_mov_b32_dpp v18, v17 quad_perm:[1,0,3,2] row_mask:0xf bank_mask:0xf
	s_waitcnt lgkmcnt(0)
	v_lshl_or_b32 v160, v0, 8, v82
	v_lshl_add_u64 v[0:1], s[12:13], 0, v[160:161]
	s_and_saveexec_b64 s[2:3], vcc
	s_cbranch_execz .LBB0_672
	s_waitcnt lgkmcnt(0)
	v_cvt_pk_bf16_f32 v17, v17, v18
	global_store_dword v[0:1], v17, off
.LBB0_672:
	s_or_b64 exec, exec, s[2:3]
	v_mul_f32_e32 v17, v34, v16
	s_waitcnt lgkmcnt(0)
	s_nop 1
	v_mov_b32_dpp v18, v17 quad_perm:[1,0,3,2] row_mask:0xf bank_mask:0xf
	s_and_saveexec_b64 s[2:3], vcc
	s_cbranch_execz .LBB0_674
	s_waitcnt lgkmcnt(0)
	v_cvt_pk_bf16_f32 v17, v17, v18
	global_store_dword v[0:1], v17, off offset:64
.LBB0_674:
	s_or_b64 exec, exec, s[2:3]
	v_mul_f32_e32 v17, v50, v16
	s_waitcnt lgkmcnt(0)
	s_nop 1
	v_mov_b32_dpp v18, v17 quad_perm:[1,0,3,2] row_mask:0xf bank_mask:0xf
	s_and_saveexec_b64 s[2:3], vcc
	s_cbranch_execz .LBB0_676
	s_waitcnt lgkmcnt(0)
	v_cvt_pk_bf16_f32 v17, v17, v18
	global_store_dword v[0:1], v17, off offset:128
.LBB0_676:
	s_or_b64 exec, exec, s[2:3]
	v_mul_f32_e32 v2, v2, v16
	s_nop 1
	v_mov_b32_dpp v16, v2 quad_perm:[1,0,3,2] row_mask:0xf bank_mask:0xf
	s_and_saveexec_b64 s[2:3], vcc
	s_cbranch_execz .LBB0_678
	s_waitcnt lgkmcnt(0)
	v_cvt_pk_bf16_f32 v2, v2, v16
	global_store_dword v[0:1], v2, off offset:192
.LBB0_678:
	s_or_b64 exec, exec, s[2:3]
	v_rcp_f32_e32 v2, v79
	ds_read_b32 v0, v83 offset:268
	s_waitcnt lgkmcnt(0)
	v_mul_f32_e32 v16, v19, v2
	s_nop 1
	v_mov_b32_dpp v17, v16 quad_perm:[1,0,3,2] row_mask:0xf bank_mask:0xf
	s_waitcnt lgkmcnt(0)
	v_lshl_or_b32 v160, v0, 8, v82
	v_lshl_add_u64 v[0:1], s[12:13], 0, v[160:161]
	s_and_saveexec_b64 s[2:3], vcc
	s_cbranch_execz .LBB0_680
	s_waitcnt lgkmcnt(0)
	v_cvt_pk_bf16_f32 v16, v16, v17
	global_store_dword v[0:1], v16, off
.LBB0_680:
	s_or_b64 exec, exec, s[2:3]
	v_mul_f32_e32 v16, v35, v2
	s_waitcnt lgkmcnt(0)
	s_nop 1
	v_mov_b32_dpp v17, v16 quad_perm:[1,0,3,2] row_mask:0xf bank_mask:0xf
	s_and_saveexec_b64 s[2:3], vcc
	s_cbranch_execz .LBB0_682
	s_waitcnt lgkmcnt(0)
	v_cvt_pk_bf16_f32 v16, v16, v17
	global_store_dword v[0:1], v16, off offset:64
.LBB0_682:
	s_or_b64 exec, exec, s[2:3]
	v_mul_f32_e32 v16, v51, v2
	s_waitcnt lgkmcnt(0)
	s_nop 1
	v_mov_b32_dpp v17, v16 quad_perm:[1,0,3,2] row_mask:0xf bank_mask:0xf
	s_and_saveexec_b64 s[2:3], vcc
	s_cbranch_execz .LBB0_684
	s_waitcnt lgkmcnt(0)
	v_cvt_pk_bf16_f32 v16, v16, v17
	global_store_dword v[0:1], v16, off offset:128
.LBB0_684:
	s_or_b64 exec, exec, s[2:3]
	v_mul_f32_e32 v2, v3, v2
	s_nop 1
	v_mov_b32_dpp v3, v2 quad_perm:[1,0,3,2] row_mask:0xf bank_mask:0xf
	s_and_saveexec_b64 s[2:3], vcc
	s_cbranch_execz .LBB0_686
	s_waitcnt lgkmcnt(0)
	v_cvt_pk_bf16_f32 v2, v2, v3
	global_store_dword v[0:1], v2, off offset:192
.LBB0_686:
	s_or_b64 exec, exec, s[2:3]
	v_rcp_f32_e32 v2, v72
	ds_read_b32 v0, v83 offset:288
	s_waitcnt lgkmcnt(0)
	v_mul_f32_e32 v3, v20, v2
	s_nop 1
	v_mov_b32_dpp v16, v3 quad_perm:[1,0,3,2] row_mask:0xf bank_mask:0xf
	s_waitcnt lgkmcnt(0)
	v_lshl_or_b32 v160, v0, 8, v82
	v_lshl_add_u64 v[0:1], s[12:13], 0, v[160:161]
	s_and_saveexec_b64 s[2:3], vcc
	s_cbranch_execz .LBB0_688
	s_waitcnt lgkmcnt(0)
	v_cvt_pk_bf16_f32 v3, v3, v16
	global_store_dword v[0:1], v3, off
.LBB0_688:
	s_or_b64 exec, exec, s[2:3]
	v_mul_f32_e32 v3, v36, v2
	s_waitcnt lgkmcnt(0)
	s_nop 1
	v_mov_b32_dpp v16, v3 quad_perm:[1,0,3,2] row_mask:0xf bank_mask:0xf
	s_and_saveexec_b64 s[2:3], vcc
	s_cbranch_execz .LBB0_690
	s_waitcnt lgkmcnt(0)
	v_cvt_pk_bf16_f32 v3, v3, v16
	global_store_dword v[0:1], v3, off offset:64
.LBB0_690:
	s_or_b64 exec, exec, s[2:3]
	v_mul_f32_e32 v3, v52, v2
	s_waitcnt lgkmcnt(0)
	s_nop 1
	v_mov_b32_dpp v16, v3 quad_perm:[1,0,3,2] row_mask:0xf bank_mask:0xf
	s_and_saveexec_b64 s[2:3], vcc
	s_cbranch_execz .LBB0_692
	s_waitcnt lgkmcnt(0)
	v_cvt_pk_bf16_f32 v3, v3, v16
	global_store_dword v[0:1], v3, off offset:128
.LBB0_692:
	s_or_b64 exec, exec, s[2:3]
	v_mul_f32_e32 v2, v4, v2
	s_nop 1
	v_mov_b32_dpp v3, v2 quad_perm:[1,0,3,2] row_mask:0xf bank_mask:0xf
	s_and_saveexec_b64 s[2:3], vcc
	s_cbranch_execz .LBB0_694
	s_waitcnt lgkmcnt(0)
	v_cvt_pk_bf16_f32 v2, v2, v3
	global_store_dword v[0:1], v2, off offset:192
.LBB0_694:
	s_or_b64 exec, exec, s[2:3]
	v_rcp_f32_e32 v2, v73
	ds_read_b32 v0, v83 offset:292
	s_waitcnt lgkmcnt(0)
	v_mul_f32_e32 v3, v21, v2
	s_nop 1
	v_mov_b32_dpp v4, v3 quad_perm:[1,0,3,2] row_mask:0xf bank_mask:0xf
	s_waitcnt lgkmcnt(0)
	v_lshl_or_b32 v160, v0, 8, v82
	v_lshl_add_u64 v[0:1], s[12:13], 0, v[160:161]
	s_and_saveexec_b64 s[2:3], vcc
	s_cbranch_execz .LBB0_696
	s_waitcnt lgkmcnt(0)
	v_cvt_pk_bf16_f32 v3, v3, v4
	global_store_dword v[0:1], v3, off
.LBB0_696:
	s_or_b64 exec, exec, s[2:3]
	v_mul_f32_e32 v3, v37, v2
	s_waitcnt lgkmcnt(0)
	s_nop 1
	v_mov_b32_dpp v4, v3 quad_perm:[1,0,3,2] row_mask:0xf bank_mask:0xf
	s_and_saveexec_b64 s[2:3], vcc
	s_cbranch_execz .LBB0_698
	s_waitcnt lgkmcnt(0)
	v_cvt_pk_bf16_f32 v3, v3, v4
	global_store_dword v[0:1], v3, off offset:64
.LBB0_698:
	s_or_b64 exec, exec, s[2:3]
	v_mul_f32_e32 v3, v53, v2
	s_waitcnt lgkmcnt(0)
	s_nop 1
	v_mov_b32_dpp v4, v3 quad_perm:[1,0,3,2] row_mask:0xf bank_mask:0xf
	s_and_saveexec_b64 s[2:3], vcc
	s_cbranch_execz .LBB0_700
	s_waitcnt lgkmcnt(0)
	v_cvt_pk_bf16_f32 v3, v3, v4
	global_store_dword v[0:1], v3, off offset:128
.LBB0_700:
	s_or_b64 exec, exec, s[2:3]
	v_mul_f32_e32 v2, v5, v2
	s_nop 1
	v_mov_b32_dpp v3, v2 quad_perm:[1,0,3,2] row_mask:0xf bank_mask:0xf
	s_and_saveexec_b64 s[2:3], vcc
	s_cbranch_execz .LBB0_702
	s_waitcnt lgkmcnt(0)
	v_cvt_pk_bf16_f32 v2, v2, v3
	global_store_dword v[0:1], v2, off offset:192
.LBB0_702:
	s_or_b64 exec, exec, s[2:3]
	v_rcp_f32_e32 v2, v74
	ds_read_b32 v0, v83 offset:296
	s_waitcnt lgkmcnt(0)
	v_mul_f32_e32 v3, v22, v2
	s_nop 1
	v_mov_b32_dpp v4, v3 quad_perm:[1,0,3,2] row_mask:0xf bank_mask:0xf
	s_waitcnt lgkmcnt(0)
	v_lshl_or_b32 v160, v0, 8, v82
	v_lshl_add_u64 v[0:1], s[12:13], 0, v[160:161]
	s_and_saveexec_b64 s[2:3], vcc
	s_cbranch_execz .LBB0_704
	s_waitcnt lgkmcnt(0)
	v_cvt_pk_bf16_f32 v3, v3, v4
	global_store_dword v[0:1], v3, off
.LBB0_704:
	s_or_b64 exec, exec, s[2:3]
	v_mul_f32_e32 v3, v38, v2
	s_waitcnt lgkmcnt(0)
	s_nop 1
	v_mov_b32_dpp v4, v3 quad_perm:[1,0,3,2] row_mask:0xf bank_mask:0xf
	s_and_saveexec_b64 s[2:3], vcc
	s_cbranch_execz .LBB0_706
	s_waitcnt lgkmcnt(0)
	v_cvt_pk_bf16_f32 v3, v3, v4
	global_store_dword v[0:1], v3, off offset:64
.LBB0_706:
	s_or_b64 exec, exec, s[2:3]
	v_mul_f32_e32 v3, v54, v2
	s_waitcnt lgkmcnt(0)
	s_nop 1
	v_mov_b32_dpp v4, v3 quad_perm:[1,0,3,2] row_mask:0xf bank_mask:0xf
	s_and_saveexec_b64 s[2:3], vcc
	s_cbranch_execz .LBB0_708
	s_waitcnt lgkmcnt(0)
	v_cvt_pk_bf16_f32 v3, v3, v4
	global_store_dword v[0:1], v3, off offset:128
.LBB0_708:
	s_or_b64 exec, exec, s[2:3]
	v_mul_f32_e32 v2, v6, v2
	s_nop 1
	v_mov_b32_dpp v3, v2 quad_perm:[1,0,3,2] row_mask:0xf bank_mask:0xf
	s_and_saveexec_b64 s[2:3], vcc
	s_cbranch_execz .LBB0_710
	s_waitcnt lgkmcnt(0)
	v_cvt_pk_bf16_f32 v2, v2, v3
	global_store_dword v[0:1], v2, off offset:192
.LBB0_710:
	s_or_b64 exec, exec, s[2:3]
	v_rcp_f32_e32 v2, v75
	ds_read_b32 v0, v83 offset:300
	s_waitcnt lgkmcnt(0)
	v_mul_f32_e32 v3, v23, v2
	s_nop 1
	v_mov_b32_dpp v4, v3 quad_perm:[1,0,3,2] row_mask:0xf bank_mask:0xf
	s_waitcnt lgkmcnt(0)
	v_lshl_or_b32 v160, v0, 8, v82
	v_lshl_add_u64 v[0:1], s[12:13], 0, v[160:161]
	s_and_saveexec_b64 s[2:3], vcc
	s_cbranch_execz .LBB0_712
	s_waitcnt lgkmcnt(0)
	v_cvt_pk_bf16_f32 v3, v3, v4
	global_store_dword v[0:1], v3, off
.LBB0_712:
	s_or_b64 exec, exec, s[2:3]
	v_mul_f32_e32 v3, v39, v2
	s_waitcnt lgkmcnt(0)
	s_nop 1
	v_mov_b32_dpp v4, v3 quad_perm:[1,0,3,2] row_mask:0xf bank_mask:0xf
	s_and_saveexec_b64 s[2:3], vcc
	s_cbranch_execz .LBB0_714
	s_waitcnt lgkmcnt(0)
	v_cvt_pk_bf16_f32 v3, v3, v4
	global_store_dword v[0:1], v3, off offset:64
.LBB0_714:
	s_or_b64 exec, exec, s[2:3]
	v_mul_f32_e32 v3, v55, v2
	s_waitcnt lgkmcnt(0)
	s_nop 1
	v_mov_b32_dpp v4, v3 quad_perm:[1,0,3,2] row_mask:0xf bank_mask:0xf
	s_and_saveexec_b64 s[2:3], vcc
	s_cbranch_execz .LBB0_716
	s_waitcnt lgkmcnt(0)
	v_cvt_pk_bf16_f32 v3, v3, v4
	global_store_dword v[0:1], v3, off offset:128
.LBB0_716:
	s_or_b64 exec, exec, s[2:3]
	v_mul_f32_e32 v2, v7, v2
	s_nop 1
	v_mov_b32_dpp v3, v2 quad_perm:[1,0,3,2] row_mask:0xf bank_mask:0xf
	s_and_saveexec_b64 s[2:3], vcc
	s_cbranch_execz .LBB0_718
	s_waitcnt lgkmcnt(0)
	v_cvt_pk_bf16_f32 v2, v2, v3
	global_store_dword v[0:1], v2, off offset:192
.LBB0_718:
	s_or_b64 exec, exec, s[2:3]
	v_rcp_f32_e32 v2, v68
	ds_read_b32 v0, v83 offset:320
	s_waitcnt lgkmcnt(0)
	v_mul_f32_e32 v3, v24, v2
	s_nop 1
	v_mov_b32_dpp v4, v3 quad_perm:[1,0,3,2] row_mask:0xf bank_mask:0xf
	s_waitcnt lgkmcnt(0)
	v_lshl_or_b32 v160, v0, 8, v82
	v_lshl_add_u64 v[0:1], s[12:13], 0, v[160:161]
	s_and_saveexec_b64 s[2:3], vcc
	s_cbranch_execz .LBB0_720
	s_waitcnt lgkmcnt(0)
	v_cvt_pk_bf16_f32 v3, v3, v4
	global_store_dword v[0:1], v3, off
.LBB0_720:
	s_or_b64 exec, exec, s[2:3]
	v_mul_f32_e32 v3, v40, v2
	s_waitcnt lgkmcnt(0)
	s_nop 1
	v_mov_b32_dpp v4, v3 quad_perm:[1,0,3,2] row_mask:0xf bank_mask:0xf
	s_and_saveexec_b64 s[2:3], vcc
	s_cbranch_execz .LBB0_722
	s_waitcnt lgkmcnt(0)
	v_cvt_pk_bf16_f32 v3, v3, v4
	global_store_dword v[0:1], v3, off offset:64
.LBB0_722:
	s_or_b64 exec, exec, s[2:3]
	v_mul_f32_e32 v3, v56, v2
	s_waitcnt lgkmcnt(0)
	s_nop 1
	v_mov_b32_dpp v4, v3 quad_perm:[1,0,3,2] row_mask:0xf bank_mask:0xf
	s_and_saveexec_b64 s[2:3], vcc
	s_cbranch_execz .LBB0_724
	s_waitcnt lgkmcnt(0)
	v_cvt_pk_bf16_f32 v3, v3, v4
	global_store_dword v[0:1], v3, off offset:128
.LBB0_724:
	s_or_b64 exec, exec, s[2:3]
	v_mul_f32_e32 v2, v8, v2
	s_nop 1
	v_mov_b32_dpp v3, v2 quad_perm:[1,0,3,2] row_mask:0xf bank_mask:0xf
	s_and_saveexec_b64 s[2:3], vcc
	s_cbranch_execz .LBB0_726
	s_waitcnt lgkmcnt(0)
	v_cvt_pk_bf16_f32 v2, v2, v3
	global_store_dword v[0:1], v2, off offset:192
.LBB0_726:
	s_or_b64 exec, exec, s[2:3]
	v_rcp_f32_e32 v2, v69
	ds_read_b32 v0, v83 offset:324
	s_waitcnt lgkmcnt(0)
	v_mul_f32_e32 v3, v25, v2
	s_nop 1
	v_mov_b32_dpp v4, v3 quad_perm:[1,0,3,2] row_mask:0xf bank_mask:0xf
	s_waitcnt lgkmcnt(0)
	v_lshl_or_b32 v160, v0, 8, v82
	v_lshl_add_u64 v[0:1], s[12:13], 0, v[160:161]
	s_and_saveexec_b64 s[2:3], vcc
	s_cbranch_execz .LBB0_728
	s_waitcnt lgkmcnt(0)
	v_cvt_pk_bf16_f32 v3, v3, v4
	global_store_dword v[0:1], v3, off
.LBB0_728:
	s_or_b64 exec, exec, s[2:3]
	v_mul_f32_e32 v3, v41, v2
	s_waitcnt lgkmcnt(0)
	s_nop 1
	v_mov_b32_dpp v4, v3 quad_perm:[1,0,3,2] row_mask:0xf bank_mask:0xf
	s_and_saveexec_b64 s[2:3], vcc
	s_cbranch_execz .LBB0_730
	s_waitcnt lgkmcnt(0)
	v_cvt_pk_bf16_f32 v3, v3, v4
	global_store_dword v[0:1], v3, off offset:64
.LBB0_730:
	s_or_b64 exec, exec, s[2:3]
	v_mul_f32_e32 v3, v57, v2
	s_waitcnt lgkmcnt(0)
	s_nop 1
	v_mov_b32_dpp v4, v3 quad_perm:[1,0,3,2] row_mask:0xf bank_mask:0xf
	s_and_saveexec_b64 s[2:3], vcc
	s_cbranch_execz .LBB0_732
	s_waitcnt lgkmcnt(0)
	v_cvt_pk_bf16_f32 v3, v3, v4
	global_store_dword v[0:1], v3, off offset:128
.LBB0_732:
	s_or_b64 exec, exec, s[2:3]
	v_mul_f32_e32 v2, v9, v2
	s_nop 1
	v_mov_b32_dpp v3, v2 quad_perm:[1,0,3,2] row_mask:0xf bank_mask:0xf
	s_and_saveexec_b64 s[2:3], vcc
	s_cbranch_execz .LBB0_734
	s_waitcnt lgkmcnt(0)
	v_cvt_pk_bf16_f32 v2, v2, v3
	global_store_dword v[0:1], v2, off offset:192
.LBB0_734:
	s_or_b64 exec, exec, s[2:3]
	v_rcp_f32_e32 v2, v70
	ds_read_b32 v0, v83 offset:328
	s_waitcnt lgkmcnt(0)
	v_mul_f32_e32 v3, v26, v2
	s_nop 1
	v_mov_b32_dpp v4, v3 quad_perm:[1,0,3,2] row_mask:0xf bank_mask:0xf
	s_waitcnt lgkmcnt(0)
	v_lshl_or_b32 v160, v0, 8, v82
	v_lshl_add_u64 v[0:1], s[12:13], 0, v[160:161]
	s_and_saveexec_b64 s[2:3], vcc
	s_cbranch_execz .LBB0_736
	s_waitcnt lgkmcnt(0)
	v_cvt_pk_bf16_f32 v3, v3, v4
	global_store_dword v[0:1], v3, off
.LBB0_736:
	s_or_b64 exec, exec, s[2:3]
	v_mul_f32_e32 v3, v42, v2
	s_waitcnt lgkmcnt(0)
	s_nop 1
	v_mov_b32_dpp v4, v3 quad_perm:[1,0,3,2] row_mask:0xf bank_mask:0xf
	s_and_saveexec_b64 s[2:3], vcc
	s_cbranch_execz .LBB0_738
	s_waitcnt lgkmcnt(0)
	v_cvt_pk_bf16_f32 v3, v3, v4
	global_store_dword v[0:1], v3, off offset:64
.LBB0_738:
	s_or_b64 exec, exec, s[2:3]
	v_mul_f32_e32 v3, v58, v2
	s_waitcnt lgkmcnt(0)
	s_nop 1
	v_mov_b32_dpp v4, v3 quad_perm:[1,0,3,2] row_mask:0xf bank_mask:0xf
	s_and_saveexec_b64 s[2:3], vcc
	s_cbranch_execz .LBB0_740
	s_waitcnt lgkmcnt(0)
	v_cvt_pk_bf16_f32 v3, v3, v4
	global_store_dword v[0:1], v3, off offset:128
.LBB0_740:
	s_or_b64 exec, exec, s[2:3]
	v_mul_f32_e32 v2, v10, v2
	s_nop 1
	v_mov_b32_dpp v3, v2 quad_perm:[1,0,3,2] row_mask:0xf bank_mask:0xf
	s_and_saveexec_b64 s[2:3], vcc
	s_cbranch_execz .LBB0_742
	s_waitcnt lgkmcnt(0)
	v_cvt_pk_bf16_f32 v2, v2, v3
	global_store_dword v[0:1], v2, off offset:192
.LBB0_742:
	s_or_b64 exec, exec, s[2:3]
	v_rcp_f32_e32 v2, v71
	ds_read_b32 v0, v83 offset:332
	s_waitcnt lgkmcnt(0)
	v_mul_f32_e32 v3, v27, v2
	s_nop 1
	v_mov_b32_dpp v4, v3 quad_perm:[1,0,3,2] row_mask:0xf bank_mask:0xf
	s_waitcnt lgkmcnt(0)
	v_lshl_or_b32 v160, v0, 8, v82
	v_lshl_add_u64 v[0:1], s[12:13], 0, v[160:161]
	s_and_saveexec_b64 s[2:3], vcc
	s_cbranch_execz .LBB0_744
	s_waitcnt lgkmcnt(0)
	v_cvt_pk_bf16_f32 v3, v3, v4
	global_store_dword v[0:1], v3, off
.LBB0_744:
	s_or_b64 exec, exec, s[2:3]
	v_mul_f32_e32 v3, v43, v2
	s_waitcnt lgkmcnt(0)
	s_nop 1
	v_mov_b32_dpp v4, v3 quad_perm:[1,0,3,2] row_mask:0xf bank_mask:0xf
	s_and_saveexec_b64 s[2:3], vcc
	s_cbranch_execz .LBB0_746
	s_waitcnt lgkmcnt(0)
	v_cvt_pk_bf16_f32 v3, v3, v4
	global_store_dword v[0:1], v3, off offset:64
.LBB0_746:
	s_or_b64 exec, exec, s[2:3]
	v_mul_f32_e32 v3, v59, v2
	s_waitcnt lgkmcnt(0)
	s_nop 1
	v_mov_b32_dpp v4, v3 quad_perm:[1,0,3,2] row_mask:0xf bank_mask:0xf
	s_and_saveexec_b64 s[2:3], vcc
	s_cbranch_execz .LBB0_748
	s_waitcnt lgkmcnt(0)
	v_cvt_pk_bf16_f32 v3, v3, v4
	global_store_dword v[0:1], v3, off offset:128
.LBB0_748:
	s_or_b64 exec, exec, s[2:3]
	v_mul_f32_e32 v2, v11, v2
	s_nop 1
	v_mov_b32_dpp v3, v2 quad_perm:[1,0,3,2] row_mask:0xf bank_mask:0xf
	s_and_saveexec_b64 s[2:3], vcc
	s_cbranch_execz .LBB0_750
	s_waitcnt lgkmcnt(0)
	v_cvt_pk_bf16_f32 v2, v2, v3
	global_store_dword v[0:1], v2, off offset:192
.LBB0_750:
	s_or_b64 exec, exec, s[2:3]
	v_rcp_f32_e32 v2, v64
	ds_read_b32 v0, v83 offset:352
	s_waitcnt lgkmcnt(0)
	v_mul_f32_e32 v3, v28, v2
	s_nop 1
	v_mov_b32_dpp v4, v3 quad_perm:[1,0,3,2] row_mask:0xf bank_mask:0xf
	s_waitcnt lgkmcnt(0)
	v_lshl_or_b32 v160, v0, 8, v82
	v_lshl_add_u64 v[0:1], s[12:13], 0, v[160:161]
	s_and_saveexec_b64 s[2:3], vcc
	s_cbranch_execz .LBB0_752
	s_waitcnt lgkmcnt(0)
	v_cvt_pk_bf16_f32 v3, v3, v4
	global_store_dword v[0:1], v3, off
.LBB0_752:
	s_or_b64 exec, exec, s[2:3]
	v_mul_f32_e32 v3, v44, v2
	s_waitcnt lgkmcnt(0)
	s_nop 1
	v_mov_b32_dpp v4, v3 quad_perm:[1,0,3,2] row_mask:0xf bank_mask:0xf
	s_and_saveexec_b64 s[2:3], vcc
	s_cbranch_execz .LBB0_754
	s_waitcnt lgkmcnt(0)
	v_cvt_pk_bf16_f32 v3, v3, v4
	global_store_dword v[0:1], v3, off offset:64
.LBB0_754:
	s_or_b64 exec, exec, s[2:3]
	v_mul_f32_e32 v3, v60, v2
	s_waitcnt lgkmcnt(0)
	s_nop 1
	v_mov_b32_dpp v4, v3 quad_perm:[1,0,3,2] row_mask:0xf bank_mask:0xf
	s_and_saveexec_b64 s[2:3], vcc
	s_cbranch_execz .LBB0_756
	s_waitcnt lgkmcnt(0)
	v_cvt_pk_bf16_f32 v3, v3, v4
	global_store_dword v[0:1], v3, off offset:128
.LBB0_756:
	s_or_b64 exec, exec, s[2:3]
	v_mul_f32_e32 v2, v12, v2
	s_nop 1
	v_mov_b32_dpp v3, v2 quad_perm:[1,0,3,2] row_mask:0xf bank_mask:0xf
	s_and_saveexec_b64 s[2:3], vcc
	s_cbranch_execz .LBB0_758
	s_waitcnt lgkmcnt(0)
	v_cvt_pk_bf16_f32 v2, v2, v3
	global_store_dword v[0:1], v2, off offset:192
.LBB0_758:
	s_or_b64 exec, exec, s[2:3]
	v_rcp_f32_e32 v2, v65
	ds_read_b32 v0, v83 offset:356
	s_waitcnt lgkmcnt(0)
	v_mul_f32_e32 v3, v29, v2
	s_nop 1
	v_mov_b32_dpp v4, v3 quad_perm:[1,0,3,2] row_mask:0xf bank_mask:0xf
	s_waitcnt lgkmcnt(0)
	v_lshl_or_b32 v160, v0, 8, v82
	v_lshl_add_u64 v[0:1], s[12:13], 0, v[160:161]
	s_and_saveexec_b64 s[2:3], vcc
	s_cbranch_execz .LBB0_760
	s_waitcnt lgkmcnt(0)
	v_cvt_pk_bf16_f32 v3, v3, v4
	global_store_dword v[0:1], v3, off
.LBB0_760:
	s_or_b64 exec, exec, s[2:3]
	v_mul_f32_e32 v3, v45, v2
	s_waitcnt lgkmcnt(0)
	s_nop 1
	v_mov_b32_dpp v4, v3 quad_perm:[1,0,3,2] row_mask:0xf bank_mask:0xf
	s_and_saveexec_b64 s[2:3], vcc
	s_cbranch_execz .LBB0_762
	s_waitcnt lgkmcnt(0)
	v_cvt_pk_bf16_f32 v3, v3, v4
	global_store_dword v[0:1], v3, off offset:64
.LBB0_762:
	s_or_b64 exec, exec, s[2:3]
	v_mul_f32_e32 v3, v61, v2
	s_waitcnt lgkmcnt(0)
	s_nop 1
	v_mov_b32_dpp v4, v3 quad_perm:[1,0,3,2] row_mask:0xf bank_mask:0xf
	s_and_saveexec_b64 s[2:3], vcc
	s_cbranch_execz .LBB0_764
	s_waitcnt lgkmcnt(0)
	v_cvt_pk_bf16_f32 v3, v3, v4
	global_store_dword v[0:1], v3, off offset:128
.LBB0_764:
	s_or_b64 exec, exec, s[2:3]
	v_mul_f32_e32 v2, v13, v2
	s_nop 1
	v_mov_b32_dpp v3, v2 quad_perm:[1,0,3,2] row_mask:0xf bank_mask:0xf
	s_and_saveexec_b64 s[2:3], vcc
	s_cbranch_execz .LBB0_766
	s_waitcnt lgkmcnt(0)
	v_cvt_pk_bf16_f32 v2, v2, v3
	global_store_dword v[0:1], v2, off offset:192
.LBB0_766:
	s_or_b64 exec, exec, s[2:3]
	v_rcp_f32_e32 v2, v66
	ds_read_b32 v0, v83 offset:360
	s_waitcnt lgkmcnt(0)
	v_mul_f32_e32 v3, v30, v2
	s_nop 1
	v_mov_b32_dpp v4, v3 quad_perm:[1,0,3,2] row_mask:0xf bank_mask:0xf
	s_waitcnt lgkmcnt(0)
	v_lshl_or_b32 v160, v0, 8, v82
	v_lshl_add_u64 v[0:1], s[12:13], 0, v[160:161]
	s_and_saveexec_b64 s[2:3], vcc
	s_cbranch_execz .LBB0_768
	s_waitcnt lgkmcnt(0)
	v_cvt_pk_bf16_f32 v3, v3, v4
	global_store_dword v[0:1], v3, off
.LBB0_768:
	s_or_b64 exec, exec, s[2:3]
	v_mul_f32_e32 v3, v46, v2
	s_waitcnt lgkmcnt(0)
	s_nop 1
	v_mov_b32_dpp v4, v3 quad_perm:[1,0,3,2] row_mask:0xf bank_mask:0xf
	s_and_saveexec_b64 s[2:3], vcc
	s_cbranch_execz .LBB0_770
	s_waitcnt lgkmcnt(0)
	v_cvt_pk_bf16_f32 v3, v3, v4
	global_store_dword v[0:1], v3, off offset:64
.LBB0_770:
	s_or_b64 exec, exec, s[2:3]
	v_mul_f32_e32 v3, v62, v2
	s_waitcnt lgkmcnt(0)
	s_nop 1
	v_mov_b32_dpp v4, v3 quad_perm:[1,0,3,2] row_mask:0xf bank_mask:0xf
	s_and_saveexec_b64 s[2:3], vcc
	s_cbranch_execz .LBB0_772
	s_waitcnt lgkmcnt(0)
	v_cvt_pk_bf16_f32 v3, v3, v4
	global_store_dword v[0:1], v3, off offset:128
.LBB0_772:
	s_or_b64 exec, exec, s[2:3]
	v_mul_f32_e32 v2, v14, v2
	s_nop 1
	v_mov_b32_dpp v3, v2 quad_perm:[1,0,3,2] row_mask:0xf bank_mask:0xf
	s_and_saveexec_b64 s[2:3], vcc
	s_cbranch_execz .LBB0_774
	s_waitcnt lgkmcnt(0)
	v_cvt_pk_bf16_f32 v2, v2, v3
	global_store_dword v[0:1], v2, off offset:192
.LBB0_774:
	s_or_b64 exec, exec, s[2:3]
	v_rcp_f32_e32 v2, v67
	ds_read_b32 v0, v83 offset:364
	s_waitcnt lgkmcnt(0)
	v_mul_f32_e32 v3, v31, v2
	s_nop 1
	v_mov_b32_dpp v4, v3 quad_perm:[1,0,3,2] row_mask:0xf bank_mask:0xf
	s_waitcnt lgkmcnt(0)
	v_lshl_or_b32 v160, v0, 8, v82
	v_lshl_add_u64 v[0:1], s[12:13], 0, v[160:161]
	s_and_saveexec_b64 s[2:3], vcc
	s_cbranch_execz .LBB0_776
	s_waitcnt lgkmcnt(0)
	v_cvt_pk_bf16_f32 v3, v3, v4
	global_store_dword v[0:1], v3, off
.LBB0_776:
	s_or_b64 exec, exec, s[2:3]
	v_mul_f32_e32 v3, v47, v2
	s_waitcnt lgkmcnt(0)
	s_nop 1
	v_mov_b32_dpp v4, v3 quad_perm:[1,0,3,2] row_mask:0xf bank_mask:0xf
	s_and_saveexec_b64 s[2:3], vcc
	s_cbranch_execz .LBB0_778
	s_waitcnt lgkmcnt(0)
	v_cvt_pk_bf16_f32 v3, v3, v4
	global_store_dword v[0:1], v3, off offset:64
.LBB0_778:
	s_or_b64 exec, exec, s[2:3]
	v_mul_f32_e32 v3, v63, v2
	s_waitcnt lgkmcnt(0)
	s_nop 1
	v_mov_b32_dpp v4, v3 quad_perm:[1,0,3,2] row_mask:0xf bank_mask:0xf
	s_and_saveexec_b64 s[2:3], vcc
	s_cbranch_execz .LBB0_780
	s_waitcnt lgkmcnt(0)
	v_cvt_pk_bf16_f32 v3, v3, v4
	global_store_dword v[0:1], v3, off offset:128
.LBB0_780:
	s_or_b64 exec, exec, s[2:3]
	v_mul_f32_e32 v2, v15, v2
	s_nop 1
	v_mov_b32_dpp v3, v2 quad_perm:[1,0,3,2] row_mask:0xf bank_mask:0xf
	s_and_saveexec_b64 s[2:3], vcc
	s_cbranch_execz .LBB0_606
	s_waitcnt lgkmcnt(0)
	v_cvt_pk_bf16_f32 v2, v2, v3
	global_store_dword v[0:1], v2, off offset:192
	s_branch .LBB0_606
